# prologue rmsnorm row loop: also hoisted the 8 loop-invariant gate-bias loads (each was load + vmcnt(0) for lane 0) out of the loop
# speedup vs baseline: 1.0220x; 1.0056x over previous
; #define LAS __attribute__((address_space(3)))
; __device__ __forceinline__ void prologue_phase(const Ptrs& P, LAS unsigned char* lds, int vcu, int G, int tid, int lane, int wave) {
;     ...
;     LAS float* wg = (LAS float*)lds;
;     for (int i = tid; i < DM * 8; i += 512) wg[i] = P.in[2][(size_t)(i >> 3) * IN0 + PROJW + (i & 7)];
;     __syncthreads();
;     bf16_t* XN = (bf16_t*)(ws + WS_XN); float* gates = (float*)(ws + WS_GATES);
;     f32x4 vn[8];
;     if (gw < MTOK) { const f32x4* xr = (const f32x4*)(P.in[0] + (size_t)gw * DM) + lane;
; #pragma unroll
;         for (int j = 0; j < 8; ++j) vn[j] = xr[64 * j]; }
;     for (int m = gw; m < MTOK; m += NGW) {
;         f32x4 v[8];
; #pragma unroll
;         for (int j = 0; j < 8; ++j) v[j] = vn[j];
;         if (m + NGW < MTOK) { const f32x4* xr = (const f32x4*)(P.in[0] + (size_t)(m + NGW) * DM) + lane;
; #pragma unroll
;             for (int j = 0; j < 8; ++j) vn[j] = xr[64 * j]; }
;     ...
;         if (lane == 0) {
; #pragma unroll
;             for (int q = 0; q < 8; ++q) gates[(size_t)m * 8 + q] = a[q] + P.in[3][q]; }
.LBB0_49:
	s_or_b64 exec, exec, s[0:1]
	s_cmpk_lt_i32 s40, 0x4000
	v_mbcnt_lo_u32_b32 v205, -1, 0
	s_waitcnt lgkmcnt(0)
	s_barrier
	s_cbranch_scc0 .LBB0_56
	s_ashr_i32 s41, s40, 31
	s_lshl_b64 s[0:1], s[40:41], 13
	s_add_u32 s0, s20, s0
	s_addc_u32 s1, s21, s1
	v_lshlrev_b32_e32 v66, 4, v1
	v_mov_b32_e32 v67, 0
	v_lshl_add_u64 v[2:3], s[0:1], 0, v[66:67]
	s_movk_i32 s3, 0x1000
	v_add_co_u32_e32 v2, vcc, s3, v2
	v_lshl_add_u64 v[68:69], s[22:23], 0, v[66:67]
	s_nop 0
	v_addc_co_u32_e32 v3, vcc, 0, v3, vcc
	global_load_dwordx4 v[34:37], v[2:3], off offset:3072
	global_load_dwordx4 v[38:41], v[2:3], off offset:2048
	global_load_dwordx4 v[42:45], v[2:3], off offset:1024
	global_load_dwordx4 v[46:49], v[2:3], off
	global_load_dwordx4 v[50:53], v66, s[0:1] offset:3072
	global_load_dwordx4 v[54:57], v66, s[0:1] offset:2048
	global_load_dwordx4 v[58:61], v66, s[0:1] offset:1024
	global_load_dwordx4 v[62:65], v66, s[0:1]
	v_mbcnt_hi_u32_b32 v2, -1, v205
	v_and_b32_e32 v3, 64, v2
	v_add_u32_e32 v3, 64, v3
	v_xor_b32_e32 v4, 1, v2
	v_cmp_lt_i32_e32 vcc, v4, v3
	s_mov_b64 s[8:9], 0x1400
	v_lshl_add_u64 v[72:73], v[68:69], 0, s[8:9]
	v_cndmask_b32_e32 v4, v2, v4, vcc
	v_lshlrev_b32_e32 v84, 2, v4
	v_xor_b32_e32 v4, 2, v2
	v_cmp_lt_i32_e32 vcc, v4, v3
	s_mov_b64 s[8:9], 0x1800
	v_lshl_add_u64 v[74:75], v[68:69], 0, s[8:9]
	v_cndmask_b32_e32 v4, v2, v4, vcc
	v_lshlrev_b32_e32 v85, 2, v4
	v_xor_b32_e32 v4, 4, v2
	v_cmp_lt_i32_e32 vcc, v4, v3
	s_mov_b64 s[8:9], 0x1c00
	v_lshl_add_u64 v[76:77], v[68:69], 0, s[8:9]
	v_cndmask_b32_e32 v4, v2, v4, vcc
	v_lshlrev_b32_e32 v86, 2, v4
	v_xor_b32_e32 v4, 8, v2
	v_cmp_lt_i32_e32 vcc, v4, v3
	v_readlane_b32 s8, v247, 0
	s_ashr_i32 s3, s2, 31
	v_cndmask_b32_e32 v4, v2, v4, vcc
	s_ashr_i32 s7, s8, 31
	v_lshlrev_b32_e32 v87, 2, v4
	v_xor_b32_e32 v4, 16, v2
	s_add_u32 s2, s2, s8
	v_cmp_lt_i32_e32 vcc, v4, v3
	s_addc_u32 s3, s3, s7
	s_add_i32 s12, s40, s28
	v_cndmask_b32_e32 v4, v2, v4, vcc
	s_ashr_i32 s29, s28, 31
	s_ashr_i32 s13, s12, 31
	v_lshlrev_b32_e32 v88, 2, v4
	v_xor_b32_e32 v4, 32, v2
	s_lshl_b64 s[8:9], s[2:3], 5
	s_lshl_b64 s[10:11], s[28:29], 5
	s_lshl_b64 s[12:13], s[12:13], 13
	v_cmp_lt_i32_e32 vcc, v4, v3
	s_add_u32 s12, s20, s12
	s_addc_u32 s13, s21, s13
	v_cndmask_b32_e32 v2, v2, v4, vcc
	v_lshlrev_b32_e32 v89, 2, v2
	s_mov_b64 s[4:5], 0x1000
	v_lshl_add_u64 v[2:3], s[12:13], 0, v[66:67]
	s_lshl_b64 s[2:3], s[2:3], 12
	v_lshl_add_u64 v[78:79], v[2:3], 0, s[4:5]
	v_lshl_or_b32 v2, v1, 3, s2
	v_mov_b32_e32 v3, s3
	s_mov_b64 s[2:3], 0xd080800
	v_lshl_add_u64 v[80:81], v[2:3], 0, s[2:3]
	v_cmp_eq_u32_e64 s[0:1], 0, v1
	v_lshl_add_u32 v90, v1, 7, 0
	v_lshl_add_u64 v[70:71], v[68:69], 0, s[4:5]
	s_lshl_b64 s[12:13], s[28:29], 13
	s_lshl_b64 s[14:15], s[28:29], 12
	v_mov_b32_e32 v1, 0x358637bd
	s_mov_b32 s2, 0xf800000
	v_mov_b32_e32 v66, 0x260
	v_mov_b32_e32 v91, 0x400000
	s_waitcnt vmcnt(7)
	v_mov_b64_e32 v[2:3], v[34:35]
	s_waitcnt vmcnt(6)
	v_mov_b64_e32 v[6:7], v[38:39]
	s_waitcnt vmcnt(5)
	v_mov_b64_e32 v[10:11], v[42:43]
	s_waitcnt vmcnt(4)
	v_mov_b64_e32 v[14:15], v[46:47]
	s_waitcnt vmcnt(3)
	v_mov_b64_e32 v[18:19], v[50:51]
	s_waitcnt vmcnt(2)
	v_mov_b64_e32 v[22:23], v[54:55]
	s_waitcnt vmcnt(1)
	v_mov_b64_e32 v[26:27], v[58:59]
	s_waitcnt vmcnt(0)
	v_mov_b64_e32 v[30:31], v[62:63]
	v_mov_b64_e32 v[4:5], v[36:37]
	v_mov_b64_e32 v[8:9], v[40:41]
	v_mov_b64_e32 v[12:13], v[44:45]
	v_mov_b64_e32 v[16:17], v[48:49]
	v_mov_b64_e32 v[20:21], v[52:53]
	v_mov_b64_e32 v[24:25], v[56:57]
	v_mov_b64_e32 v[28:29], v[60:61]
	v_mov_b64_e32 v[32:33], v[64:65]
	global_load_dwordx4 v[116:119], v[68:69], off
	global_load_dwordx4 v[120:123], v[68:69], off offset:1024
	global_load_dwordx4 v[124:127], v[68:69], off offset:2048
	global_load_dwordx4 v[128:131], v[68:69], off offset:3072
	global_load_dwordx4 v[132:135], v[70:71], off
	global_load_dwordx4 v[136:139], v[72:73], off
	global_load_dwordx4 v[140:143], v[74:75], off
	global_load_dwordx4 v[144:147], v[76:77], off
	global_load_dword v148, v67, s[26:27]
	global_load_dword v149, v67, s[26:27] offset:4
	global_load_dword v150, v67, s[26:27] offset:8
	global_load_dword v151, v67, s[26:27] offset:12
	global_load_dword v152, v67, s[26:27] offset:16
	global_load_dword v153, v67, s[26:27] offset:20
	global_load_dword v154, v67, s[26:27] offset:24
	global_load_dword v155, v67, s[26:27] offset:28
	s_waitcnt vmcnt(0)
	s_branch .LBB0_52

; __device__ __forceinline__ unsigned pk2(float lo, float hi) { return pg8::cvt_pk_bf16(lo, hi); }
; __device__ __forceinline__ void rms_row_loaded(const float* __restrict__ g, bf16_t* orow, int lane, f32x4 (&v)[8]) {
;     float s = 0.f;
; #pragma unroll
;     for (int j = 0; j < 8; ++j) s += (v[j].x * v[j].x + v[j].y * v[j].y) + (v[j].z * v[j].z + v[j].w * v[j].w);
;     const float rstd = 1.0f / sqrtf(wave_sum(s) * (1.0f / DM) + EPS);
;     const f32x4* gr = (const f32x4*)g + lane;
;     u32x2* o8 = (u32x2*)orow + lane;
; #pragma unroll
;     for (int j = 0; j < 8; ++j) { v[j] = v[j] * rstd * gr[64 * j]; u32x2 w; w.x = pk2(v[j].x, v[j].y); w.y = pk2(v[j].z, v[j].w); o8[64 * j] = w; }
.LBB0_54:
	v_mov_b32_e32 v92, v59
	v_mov_b32_e32 v93, v63
	v_mov_b32_e32 v82, v58
	v_mov_b32_e32 v83, v62
	v_pk_mul_f32 v[92:93], v[92:93], v[92:93]
	v_mov_b32_e32 v94, v61
	v_mov_b32_e32 v95, v65
	v_pk_fma_f32 v[82:83], v[82:83], v[82:83], v[92:93]
	v_mov_b32_e32 v92, v60
	v_mov_b32_e32 v93, v64
	v_pk_mul_f32 v[94:95], v[94:95], v[94:95]
	s_nop 0
	v_pk_fma_f32 v[92:93], v[92:93], v[92:93], v[94:95]
	v_pk_mul_f32 v[94:95], v[54:55], v[54:55]
	v_pk_add_f32 v[82:83], v[82:83], v[92:93]
	v_pk_mul_f32 v[92:93], v[56:57], v[56:57]
	v_pk_add_f32 v[82:83], v[82:83], v[82:83] op_sel_hi:[0,1]
	v_pk_mov_b32 v[96:97], v[94:95], v[92:93] op_sel:[1,0]
	v_mov_b32_e32 v95, v93
	v_mul_f32_e32 v82, v50, v50
	v_pk_add_f32 v[92:93], v[96:97], v[94:95]
	v_pk_fma_f32 v[94:95], v[50:51], v[50:51], v[82:83] op_sel_hi:[1,1,0]
	v_mul_f32_e32 v82, v52, v52
	v_pk_add_f32 v[92:93], v[92:93], v[92:93] op_sel_hi:[0,1]
	v_pk_fma_f32 v[96:97], v[52:53], v[52:53], v[82:83] op_sel_hi:[1,1,0]
	v_mul_f32_e32 v94, v46, v46
	v_mul_f32_e32 v96, v47, v47
	v_mul_f32_e32 v92, v48, v48
	v_mul_f32_e32 v82, v49, v49
	v_pk_add_f32 v[94:95], v[94:95], v[96:97]
	v_pk_add_f32 v[82:83], v[92:93], v[82:83]
	v_pk_mul_f32 v[92:93], v[44:45], v[44:45]
	v_pk_add_f32 v[82:83], v[94:95], v[82:83]
	v_pk_mul_f32 v[94:95], v[42:43], v[42:43]
	v_pk_add_f32 v[82:83], v[82:83], v[82:83] op_sel_hi:[0,1]
	v_pk_mov_b32 v[96:97], v[94:95], v[92:93] op_sel:[1,0]
	v_mov_b32_e32 v95, v93
	v_mul_f32_e32 v82, v38, v38
	v_pk_add_f32 v[92:93], v[96:97], v[94:95]
	v_pk_fma_f32 v[94:95], v[38:39], v[38:39], v[82:83] op_sel_hi:[1,1,0]
	v_mul_f32_e32 v82, v40, v40
	v_pk_add_f32 v[92:93], v[92:93], v[92:93] op_sel_hi:[0,1]
	v_pk_fma_f32 v[96:97], v[40:41], v[40:41], v[82:83] op_sel_hi:[1,1,0]
	v_mul_f32_e32 v94, v34, v34
	v_mul_f32_e32 v96, v35, v35
	v_mul_f32_e32 v92, v36, v36
	v_mul_f32_e32 v82, v37, v37
	v_pk_add_f32 v[94:95], v[94:95], v[96:97]
	v_pk_add_f32 v[82:83], v[92:93], v[82:83]
	s_nop 0
	v_pk_add_f32 v[82:83], v[94:95], v[82:83]
	s_nop 0
	v_add_f32_e32 v82, v82, v83
	ds_bpermute_b32 v83, v84, v82
	s_waitcnt lgkmcnt(0)
	v_add_f32_e32 v82, v82, v83
	ds_bpermute_b32 v83, v85, v82
	s_waitcnt lgkmcnt(0)
	v_add_f32_e32 v82, v82, v83
	ds_bpermute_b32 v83, v86, v82
	s_waitcnt lgkmcnt(0)
	v_add_f32_e32 v82, v82, v83
	ds_bpermute_b32 v83, v87, v82
	s_waitcnt lgkmcnt(0)
	v_add_f32_e32 v82, v82, v83
	ds_bpermute_b32 v83, v88, v82
	s_waitcnt lgkmcnt(0)
	v_add_f32_e32 v82, v82, v83
	ds_bpermute_b32 v83, v89, v82
	s_waitcnt lgkmcnt(0)
	v_add_f32_e32 v82, v82, v83
	v_fmamk_f32 v82, v82, 0x3a000000, v1
	v_cmp_gt_f32_e32 vcc, s2, v82
	v_mul_f32_e32 v83, 0x4f800000, v82
	s_nop 0
	v_cndmask_b32_e32 v82, v82, v83, vcc
	v_sqrt_f32_e32 v83, v82
	s_nop 0
	v_add_u32_e32 v92, -1, v83
	v_fma_f32 v93, -v92, v83, v82
	v_cmp_ge_f32_e64 s[4:5], 0, v93
	v_add_u32_e32 v93, 1, v83
	s_nop 0
	v_cndmask_b32_e64 v92, v83, v92, s[4:5]
	v_fma_f32 v83, -v93, v83, v82
	v_cmp_lt_f32_e64 s[4:5], 0, v83
	s_nop 1
	v_cndmask_b32_e64 v83, v92, v93, s[4:5]
	v_mul_f32_e32 v92, 0x37800000, v83
	v_cndmask_b32_e32 v83, v83, v92, vcc
	v_cmp_class_f32_e32 vcc, v82, v66
	s_nop 1
	v_cndmask_b32_e32 v82, v83, v82, vcc
	v_div_scale_f32 v83, s[4:5], v82, v82, 1.0
	v_rcp_f32_e32 v92, v83
	s_nop 0
	v_fma_f32 v93, -v83, v92, 1.0
	v_fmac_f32_e32 v92, v93, v92
	v_div_scale_f32 v93, vcc, 1.0, v82, 1.0
	v_mul_f32_e32 v94, v93, v92
	v_fma_f32 v95, -v83, v94, v93
	v_fmac_f32_e32 v94, v95, v92
	v_fma_f32 v83, -v83, v94, v93
	v_div_fmas_f32 v83, v83, v92, v94
	v_div_fixup_f32 v96, v83, v82, 1.0
	v_pk_mul_f32 v[98:99], v[62:63], v[96:97] op_sel_hi:[1,0]
	v_pk_mul_f32 v[62:63], v[64:65], v[96:97] op_sel_hi:[1,0]
	v_lshl_add_u64 v[82:83], s[34:35], 0, v[80:81]
	s_nop 0
	v_pk_mul_f32 v[62:63], v[118:119], v[62:63]
	v_pk_mul_f32 v[64:65], v[116:117], v[98:99]
	v_cvt_pk_bf16_f32 v93, v62, v63
	v_cvt_pk_bf16_f32 v92, v64, v65
	global_store_dwordx2 v[82:83], v[92:93], off offset:-2048
	v_pk_mul_f32 v[98:99], v[58:59], v[96:97] op_sel_hi:[1,0]
	v_pk_mul_f32 v[58:59], v[60:61], v[96:97] op_sel_hi:[1,0]
	s_nop 0
	v_pk_mul_f32 v[60:61], v[120:121], v[98:99]
	v_pk_mul_f32 v[58:59], v[122:123], v[58:59]
	v_cvt_pk_bf16_f32 v92, v60, v61
	v_cvt_pk_bf16_f32 v93, v58, v59
	global_store_dwordx2 v[82:83], v[92:93], off offset:-1536
	v_pk_mul_f32 v[98:99], v[54:55], v[96:97] op_sel_hi:[1,0]
	v_pk_mul_f32 v[54:55], v[56:57], v[96:97] op_sel_hi:[1,0]
	s_nop 0
	v_pk_mul_f32 v[56:57], v[124:125], v[98:99]
	v_pk_mul_f32 v[54:55], v[126:127], v[54:55]
	v_cvt_pk_bf16_f32 v92, v56, v57
	v_cvt_pk_bf16_f32 v93, v54, v55
	global_store_dwordx2 v[82:83], v[92:93], off offset:-1024
	v_pk_mul_f32 v[98:99], v[50:51], v[96:97] op_sel_hi:[1,0]
	v_pk_mul_f32 v[50:51], v[52:53], v[96:97] op_sel_hi:[1,0]
	s_nop 0
	v_pk_mul_f32 v[52:53], v[128:129], v[98:99]
	v_pk_mul_f32 v[50:51], v[130:131], v[50:51]
	v_cvt_pk_bf16_f32 v92, v52, v53
	v_cvt_pk_bf16_f32 v93, v50, v51
	global_store_dwordx2 v[82:83], v[92:93], off offset:-512
	v_pk_mul_f32 v[98:99], v[46:47], v[96:97] op_sel_hi:[1,0]
	v_pk_mul_f32 v[46:47], v[48:49], v[96:97] op_sel_hi:[1,0]
	s_nop 0
	v_pk_mul_f32 v[48:49], v[98:99], v[132:133]
	v_pk_mul_f32 v[46:47], v[46:47], v[134:135]
	v_cvt_pk_bf16_f32 v92, v48, v49
	v_cvt_pk_bf16_f32 v93, v46, v47
	global_store_dwordx2 v[82:83], v[92:93], off
	v_pk_mul_f32 v[98:99], v[42:43], v[96:97] op_sel_hi:[1,0]
	v_pk_mul_f32 v[42:43], v[44:45], v[96:97] op_sel_hi:[1,0]
	s_nop 0
	v_pk_mul_f32 v[44:45], v[98:99], v[136:137]
	v_pk_mul_f32 v[42:43], v[42:43], v[138:139]
	v_cvt_pk_bf16_f32 v92, v44, v45
	v_cvt_pk_bf16_f32 v93, v42, v43
	global_store_dwordx2 v[82:83], v[92:93], off offset:512
	v_pk_mul_f32 v[98:99], v[38:39], v[96:97] op_sel_hi:[1,0]
	v_pk_mul_f32 v[38:39], v[40:41], v[96:97] op_sel_hi:[1,0]
	s_nop 0
	v_pk_mul_f32 v[40:41], v[98:99], v[140:141]
	v_pk_mul_f32 v[38:39], v[38:39], v[142:143]
	v_cvt_pk_bf16_f32 v92, v40, v41
	v_cvt_pk_bf16_f32 v93, v38, v39
	global_store_dwordx2 v[82:83], v[92:93], off offset:1024
	v_pk_mul_f32 v[98:99], v[34:35], v[96:97] op_sel_hi:[1,0]
	v_pk_mul_f32 v[34:35], v[36:37], v[96:97] op_sel_hi:[1,0]
	s_nop 0
	v_pk_mul_f32 v[36:37], v[98:99], v[144:145]
	v_pk_mul_f32 v[34:35], v[34:35], v[146:147]
	v_cvt_pk_bf16_f32 v92, v36, v37
	v_cvt_pk_bf16_f32 v93, v34, v35
	global_store_dwordx2 v[82:83], v[92:93], off offset:1536
	ds_read_b128 v[96:99], v90
	ds_read_b128 v[100:103], v90 offset:16
	ds_read_b128 v[104:107], v90 offset:32
	ds_read_b128 v[108:111], v90 offset:48
	s_waitcnt lgkmcnt(3)
; #define LAS __attribute__((address_space(3)))
; __device__ __forceinline__ void prologue_phase(const Ptrs& P, LAS unsigned char* lds, int vcu, int G, int tid, int lane, int wave) {
;     ...
;         for (int j = 0; j < 8; ++j)
; #pragma unroll
;             for (int i = 0; i < 4; ++i) { const int k = 256 * j + 4 * lane + i; const f32x4 w0 = *(const LAS f32x4*)(wg + k * 8), w1 = *(const LAS f32x4*)(wg + k * 8 + 4); const float hv = v[j][i];
;                 a[0] += hv * w0.x; a[1] += hv * w0.y; a[2] += hv * w0.z; a[3] += hv * w0.w; a[4] += hv * w1.x; a[5] += hv * w1.y; a[6] += hv * w1.z; a[7] += hv * w1.w;
;                 if (i == 3) asm volatile("" ::: "memory"); }
	v_fma_f32 v96, v64, v96, 0
	v_fma_f32 v95, v64, v97, 0
	v_fma_f32 v94, v64, v98, 0
	v_fma_f32 v93, v64, v99, 0
	s_waitcnt lgkmcnt(2)
	v_fma_f32 v92, v64, v100, 0
	v_fma_f32 v83, v64, v101, 0
	v_fma_f32 v82, v64, v102, 0
	v_fma_f32 v64, v64, v103, 0
	s_waitcnt lgkmcnt(1)
	v_fmac_f32_e32 v96, v65, v104
	v_fmac_f32_e32 v95, v65, v105
	ds_read_b128 v[98:101], v90 offset:64
	ds_read_b128 v[102:105], v90 offset:80
	v_fmac_f32_e32 v94, v65, v106
	v_fmac_f32_e32 v93, v65, v107
	s_waitcnt lgkmcnt(2)
	v_fmac_f32_e32 v92, v65, v108
	v_fmac_f32_e32 v83, v65, v109
	v_fmac_f32_e32 v82, v65, v110
	v_fmac_f32_e32 v64, v65, v111
	s_waitcnt lgkmcnt(1)
	v_fmac_f32_e32 v96, v62, v98
	v_fmac_f32_e32 v95, v62, v99
	v_fmac_f32_e32 v94, v62, v100
	v_fmac_f32_e32 v93, v62, v101
	s_waitcnt lgkmcnt(0)
	v_fmac_f32_e32 v92, v62, v102
	v_fmac_f32_e32 v83, v62, v103
	v_fmac_f32_e32 v82, v62, v104
	v_fmac_f32_e32 v64, v62, v105
	ds_read_b128 v[98:101], v90 offset:96
	ds_read_b128 v[102:105], v90 offset:112
	s_waitcnt lgkmcnt(1)
	v_fmac_f32_e32 v96, v63, v98
	v_fmac_f32_e32 v95, v63, v99
	v_fmac_f32_e32 v94, v63, v100
	v_fmac_f32_e32 v93, v63, v101
	s_waitcnt lgkmcnt(0)
	v_fmac_f32_e32 v92, v63, v102
	v_fmac_f32_e32 v83, v63, v103
	v_fmac_f32_e32 v82, v63, v104
	v_fmac_f32_e32 v64, v63, v105
	ds_read_b128 v[98:101], v90 offset:8192
	ds_read_b128 v[102:105], v90 offset:8208
	ds_read_b128 v[106:109], v90 offset:8224
	ds_read_b128 v[110:113], v90 offset:8240
	s_waitcnt lgkmcnt(3)
	v_fmac_f32_e32 v96, v60, v98
	v_fmac_f32_e32 v95, v60, v99
	v_fmac_f32_e32 v94, v60, v100
	v_fmac_f32_e32 v93, v60, v101
	s_waitcnt lgkmcnt(2)
	v_fmac_f32_e32 v92, v60, v102
	v_fmac_f32_e32 v83, v60, v103
	v_fmac_f32_e32 v82, v60, v104
	v_fmac_f32_e32 v64, v60, v105
	s_waitcnt lgkmcnt(1)
	v_fmac_f32_e32 v96, v61, v106
	v_fmac_f32_e32 v95, v61, v107
	v_fmac_f32_e32 v94, v61, v108
	v_fmac_f32_e32 v93, v61, v109
	s_waitcnt lgkmcnt(0)
	v_fmac_f32_e32 v92, v61, v110
	v_fmac_f32_e32 v83, v61, v111
	v_fmac_f32_e32 v82, v61, v112
	v_fmac_f32_e32 v64, v61, v113
	ds_read_b128 v[60:63], v90 offset:8256
	ds_read_b128 v[98:101], v90 offset:8272
	s_waitcnt lgkmcnt(1)
	v_fmac_f32_e32 v96, v58, v60
	v_fmac_f32_e32 v95, v58, v61
	v_fmac_f32_e32 v94, v58, v62
	v_fmac_f32_e32 v93, v58, v63
	s_waitcnt lgkmcnt(0)
	v_fmac_f32_e32 v92, v58, v98
	v_fmac_f32_e32 v83, v58, v99
	v_fmac_f32_e32 v82, v58, v100
	v_fmac_f32_e32 v64, v58, v101
	ds_read_b128 v[60:63], v90 offset:8288
	ds_read_b128 v[98:101], v90 offset:8304
	s_waitcnt lgkmcnt(1)
	v_fmac_f32_e32 v96, v59, v60
	v_fmac_f32_e32 v95, v59, v61
	v_fmac_f32_e32 v94, v59, v62
	v_fmac_f32_e32 v93, v59, v63
	s_waitcnt lgkmcnt(0)
	v_fmac_f32_e32 v92, v59, v98
	v_fmac_f32_e32 v83, v59, v99
	v_fmac_f32_e32 v82, v59, v100
	v_fmac_f32_e32 v64, v59, v101
	ds_read_b128 v[58:61], v90 offset:16384
	ds_read_b128 v[98:101], v90 offset:16400
	ds_read_b128 v[102:105], v90 offset:16416
	ds_read_b128 v[106:109], v90 offset:16432
	s_waitcnt lgkmcnt(3)
	v_fmac_f32_e32 v96, v56, v58
	v_fmac_f32_e32 v95, v56, v59
	v_fmac_f32_e32 v94, v56, v60
	v_fmac_f32_e32 v93, v56, v61
	s_waitcnt lgkmcnt(2)
	v_fmac_f32_e32 v92, v56, v98
	v_fmac_f32_e32 v83, v56, v99
	v_fmac_f32_e32 v82, v56, v100
	v_fmac_f32_e32 v64, v56, v101
	s_waitcnt lgkmcnt(1)
	v_fmac_f32_e32 v96, v57, v102
	v_fmac_f32_e32 v95, v57, v103
	v_fmac_f32_e32 v94, v57, v104
	v_fmac_f32_e32 v93, v57, v105
	s_waitcnt lgkmcnt(0)
	v_fmac_f32_e32 v92, v57, v106
	v_fmac_f32_e32 v83, v57, v107
	v_fmac_f32_e32 v82, v57, v108
	v_fmac_f32_e32 v64, v57, v109
	ds_read_b128 v[56:59], v90 offset:16448
	ds_read_b128 v[60:63], v90 offset:16464
	s_waitcnt lgkmcnt(1)
	v_fmac_f32_e32 v96, v54, v56
	v_fmac_f32_e32 v95, v54, v57
	v_fmac_f32_e32 v94, v54, v58
	v_fmac_f32_e32 v93, v54, v59
	s_waitcnt lgkmcnt(0)
	v_fmac_f32_e32 v92, v54, v60
	v_fmac_f32_e32 v83, v54, v61
	v_fmac_f32_e32 v82, v54, v62
	v_fmac_f32_e32 v64, v54, v63
	ds_read_b128 v[56:59], v90 offset:16480
	ds_read_b128 v[60:63], v90 offset:16496
	s_waitcnt lgkmcnt(1)
	v_fmac_f32_e32 v96, v55, v56
	v_fmac_f32_e32 v95, v55, v57
	v_fmac_f32_e32 v94, v55, v58
	v_fmac_f32_e32 v93, v55, v59
	s_waitcnt lgkmcnt(0)
	v_fmac_f32_e32 v92, v55, v60
	v_fmac_f32_e32 v83, v55, v61
	v_fmac_f32_e32 v82, v55, v62
	v_fmac_f32_e32 v64, v55, v63
	ds_read_b128 v[54:57], v90 offset:24576
	ds_read_b128 v[58:61], v90 offset:24592
	ds_read_b128 v[98:101], v90 offset:24608
	ds_read_b128 v[102:105], v90 offset:24624
	s_waitcnt lgkmcnt(3)
	v_fmac_f32_e32 v96, v52, v54
	v_fmac_f32_e32 v95, v52, v55
	v_fmac_f32_e32 v94, v52, v56
	v_fmac_f32_e32 v93, v52, v57
	s_waitcnt lgkmcnt(2)
	v_fmac_f32_e32 v92, v52, v58
	v_fmac_f32_e32 v83, v52, v59
	v_fmac_f32_e32 v82, v52, v60
	v_fmac_f32_e32 v64, v52, v61
	s_waitcnt lgkmcnt(1)
	v_fmac_f32_e32 v96, v53, v98
	v_fmac_f32_e32 v95, v53, v99
	v_fmac_f32_e32 v94, v53, v100
	v_fmac_f32_e32 v93, v53, v101
	s_waitcnt lgkmcnt(0)
	v_fmac_f32_e32 v92, v53, v102
	v_fmac_f32_e32 v83, v53, v103
	v_fmac_f32_e32 v82, v53, v104
	v_fmac_f32_e32 v64, v53, v105
	ds_read_b128 v[52:55], v90 offset:24640
	ds_read_b128 v[56:59], v90 offset:24656
	s_waitcnt lgkmcnt(1)
	v_fmac_f32_e32 v96, v50, v52
	v_fmac_f32_e32 v95, v50, v53
	v_fmac_f32_e32 v94, v50, v54
	v_fmac_f32_e32 v93, v50, v55
	s_waitcnt lgkmcnt(0)
	v_fmac_f32_e32 v92, v50, v56
	v_fmac_f32_e32 v83, v50, v57
	v_fmac_f32_e32 v82, v50, v58
	v_fmac_f32_e32 v64, v50, v59
	ds_read_b128 v[52:55], v90 offset:24672
	ds_read_b128 v[56:59], v90 offset:24688
	s_waitcnt lgkmcnt(1)
	v_fmac_f32_e32 v96, v51, v52
	v_fmac_f32_e32 v95, v51, v53
	v_fmac_f32_e32 v94, v51, v54
	v_fmac_f32_e32 v93, v51, v55
	s_waitcnt lgkmcnt(0)
; #define LAS __attribute__((address_space(3)))
; __device__ __forceinline__ void prologue_phase(const Ptrs& P, LAS unsigned char* lds, int vcu, int G, int tid, int lane, int wave) {
;     ...
;         for (int j = 0; j < 8; ++j)
; #pragma unroll
;             for (int i = 0; i < 4; ++i) { const int k = 256 * j + 4 * lane + i; const f32x4 w0 = *(const LAS f32x4*)(wg + k * 8), w1 = *(const LAS f32x4*)(wg + k * 8 + 4); const float hv = v[j][i];
;                 a[0] += hv * w0.x; a[1] += hv * w0.y; a[2] += hv * w0.z; a[3] += hv * w0.w; a[4] += hv * w1.x; a[5] += hv * w1.y; a[6] += hv * w1.z; a[7] += hv * w1.w;
;                 if (i == 3) asm volatile("" ::: "memory"); }
	v_fmac_f32_e32 v92, v51, v56
	v_fmac_f32_e32 v83, v51, v57
	v_fmac_f32_e32 v82, v51, v58
	v_fmac_f32_e32 v64, v51, v59
	ds_read_b128 v[50:53], v90 offset:32768
	ds_read_b128 v[54:57], v90 offset:32784
	ds_read_b128 v[58:61], v90 offset:32800
	ds_read_b128 v[98:101], v90 offset:32816
	s_waitcnt lgkmcnt(3)
	v_fmac_f32_e32 v96, v48, v50
	v_fmac_f32_e32 v95, v48, v51
	v_fmac_f32_e32 v94, v48, v52
	v_fmac_f32_e32 v93, v48, v53
	s_waitcnt lgkmcnt(2)
	v_fmac_f32_e32 v92, v48, v54
	v_fmac_f32_e32 v83, v48, v55
	v_fmac_f32_e32 v82, v48, v56
	v_fmac_f32_e32 v64, v48, v57
	s_waitcnt lgkmcnt(1)
	v_fmac_f32_e32 v96, v49, v58
	v_fmac_f32_e32 v95, v49, v59
	v_fmac_f32_e32 v94, v49, v60
	v_fmac_f32_e32 v93, v49, v61
	s_waitcnt lgkmcnt(0)
	v_fmac_f32_e32 v92, v49, v98
	v_fmac_f32_e32 v83, v49, v99
	v_fmac_f32_e32 v82, v49, v100
	v_fmac_f32_e32 v64, v49, v101
	ds_read_b128 v[48:51], v90 offset:32832
	ds_read_b128 v[52:55], v90 offset:32848
	s_waitcnt lgkmcnt(1)
	v_fmac_f32_e32 v96, v46, v48
	v_fmac_f32_e32 v95, v46, v49
	v_fmac_f32_e32 v94, v46, v50
	v_fmac_f32_e32 v93, v46, v51
	s_waitcnt lgkmcnt(0)
	v_fmac_f32_e32 v92, v46, v52
	v_fmac_f32_e32 v83, v46, v53
	v_fmac_f32_e32 v82, v46, v54
	v_fmac_f32_e32 v64, v46, v55
	ds_read_b128 v[48:51], v90 offset:32864
	ds_read_b128 v[52:55], v90 offset:32880
	s_waitcnt lgkmcnt(1)
	v_fmac_f32_e32 v96, v47, v48
	v_fmac_f32_e32 v95, v47, v49
	v_fmac_f32_e32 v94, v47, v50
	v_fmac_f32_e32 v93, v47, v51
	s_waitcnt lgkmcnt(0)
	v_fmac_f32_e32 v92, v47, v52
	v_fmac_f32_e32 v83, v47, v53
	v_fmac_f32_e32 v82, v47, v54
	v_fmac_f32_e32 v64, v47, v55
	ds_read_b128 v[46:49], v90 offset:40960
	ds_read_b128 v[50:53], v90 offset:40976
	ds_read_b128 v[54:57], v90 offset:40992
	ds_read_b128 v[58:61], v90 offset:41008
	s_waitcnt lgkmcnt(3)
	v_fmac_f32_e32 v96, v44, v46
	v_fmac_f32_e32 v95, v44, v47
	v_fmac_f32_e32 v94, v44, v48
	v_fmac_f32_e32 v93, v44, v49
	s_waitcnt lgkmcnt(2)
	v_fmac_f32_e32 v92, v44, v50
	v_fmac_f32_e32 v83, v44, v51
	v_fmac_f32_e32 v82, v44, v52
	v_fmac_f32_e32 v64, v44, v53
	s_waitcnt lgkmcnt(1)
	v_fmac_f32_e32 v96, v45, v54
	v_fmac_f32_e32 v95, v45, v55
	v_fmac_f32_e32 v94, v45, v56
	v_fmac_f32_e32 v93, v45, v57
	s_waitcnt lgkmcnt(0)
	v_fmac_f32_e32 v92, v45, v58
	v_fmac_f32_e32 v83, v45, v59
	v_fmac_f32_e32 v82, v45, v60
	v_fmac_f32_e32 v64, v45, v61
	ds_read_b128 v[44:47], v90 offset:41024
	ds_read_b128 v[48:51], v90 offset:41040
	s_waitcnt lgkmcnt(1)
	v_fmac_f32_e32 v96, v42, v44
	v_fmac_f32_e32 v95, v42, v45
	v_fmac_f32_e32 v94, v42, v46
	v_fmac_f32_e32 v93, v42, v47
	s_waitcnt lgkmcnt(0)
	v_fmac_f32_e32 v92, v42, v48
	v_fmac_f32_e32 v83, v42, v49
	v_fmac_f32_e32 v82, v42, v50
	v_fmac_f32_e32 v64, v42, v51
	ds_read_b128 v[44:47], v90 offset:41056
	ds_read_b128 v[48:51], v90 offset:41072
	s_waitcnt lgkmcnt(1)
	v_fmac_f32_e32 v96, v43, v44
	v_fmac_f32_e32 v95, v43, v45
	v_fmac_f32_e32 v94, v43, v46
	v_fmac_f32_e32 v93, v43, v47
	s_waitcnt lgkmcnt(0)
	v_fmac_f32_e32 v92, v43, v48
	v_fmac_f32_e32 v83, v43, v49
	v_fmac_f32_e32 v82, v43, v50
	v_fmac_f32_e32 v64, v43, v51
	ds_read_b128 v[42:45], v90 offset:49152
	ds_read_b128 v[46:49], v90 offset:49168
	ds_read_b128 v[50:53], v90 offset:49184
	ds_read_b128 v[54:57], v90 offset:49200
	s_waitcnt lgkmcnt(3)
	v_fmac_f32_e32 v96, v40, v42
	v_fmac_f32_e32 v95, v40, v43
	v_fmac_f32_e32 v94, v40, v44
	v_fmac_f32_e32 v93, v40, v45
	s_waitcnt lgkmcnt(2)
	v_fmac_f32_e32 v92, v40, v46
	v_fmac_f32_e32 v83, v40, v47
	v_fmac_f32_e32 v82, v40, v48
	v_fmac_f32_e32 v64, v40, v49
	s_waitcnt lgkmcnt(1)
	v_fmac_f32_e32 v96, v41, v50
	v_fmac_f32_e32 v95, v41, v51
	v_fmac_f32_e32 v94, v41, v52
	v_fmac_f32_e32 v93, v41, v53
	s_waitcnt lgkmcnt(0)
	v_fmac_f32_e32 v92, v41, v54
	v_fmac_f32_e32 v83, v41, v55
	v_fmac_f32_e32 v82, v41, v56
	v_fmac_f32_e32 v64, v41, v57
	ds_read_b128 v[40:43], v90 offset:49216
	ds_read_b128 v[44:47], v90 offset:49232
	s_waitcnt lgkmcnt(1)
	v_fmac_f32_e32 v96, v38, v40
	v_fmac_f32_e32 v95, v38, v41
	v_fmac_f32_e32 v94, v38, v42
	v_fmac_f32_e32 v93, v38, v43
	s_waitcnt lgkmcnt(0)
	v_fmac_f32_e32 v92, v38, v44
	v_fmac_f32_e32 v83, v38, v45
	v_fmac_f32_e32 v82, v38, v46
	v_fmac_f32_e32 v64, v38, v47
	ds_read_b128 v[40:43], v90 offset:49248
	ds_read_b128 v[44:47], v90 offset:49264
	s_waitcnt lgkmcnt(1)
	v_fmac_f32_e32 v96, v39, v40
	v_fmac_f32_e32 v95, v39, v41
	v_fmac_f32_e32 v94, v39, v42
	v_fmac_f32_e32 v93, v39, v43
	s_waitcnt lgkmcnt(0)
	v_fmac_f32_e32 v92, v39, v44
	v_fmac_f32_e32 v83, v39, v45
	v_fmac_f32_e32 v82, v39, v46
	v_fmac_f32_e32 v64, v39, v47
	ds_read_b128 v[38:41], v90 offset:57344
	ds_read_b128 v[42:45], v90 offset:57360
	ds_read_b128 v[46:49], v90 offset:57376
	ds_read_b128 v[50:53], v90 offset:57392
	s_waitcnt lgkmcnt(3)
	v_fmac_f32_e32 v96, v36, v38
	v_fmac_f32_e32 v95, v36, v39
	v_fmac_f32_e32 v94, v36, v40
	v_fmac_f32_e32 v93, v36, v41
	s_waitcnt lgkmcnt(2)
	v_fmac_f32_e32 v92, v36, v42
	v_fmac_f32_e32 v83, v36, v43
	v_fmac_f32_e32 v82, v36, v44
	v_fmac_f32_e32 v64, v36, v45
	s_waitcnt lgkmcnt(1)
	v_fmac_f32_e32 v96, v37, v46
	v_fmac_f32_e32 v95, v37, v47
	v_fmac_f32_e32 v94, v37, v48
	v_fmac_f32_e32 v93, v37, v49
	s_waitcnt lgkmcnt(0)
	v_fmac_f32_e32 v92, v37, v50
	v_fmac_f32_e32 v83, v37, v51
	v_fmac_f32_e32 v82, v37, v52
	v_fmac_f32_e32 v64, v37, v53
	ds_read_b128 v[36:39], v90 offset:57408
	ds_read_b128 v[40:43], v90 offset:57424
	s_waitcnt lgkmcnt(1)
	v_fmac_f32_e32 v96, v34, v36
	v_fmac_f32_e32 v95, v34, v37
	v_fmac_f32_e32 v94, v34, v38
	v_fmac_f32_e32 v93, v34, v39
	s_waitcnt lgkmcnt(0)
; #define LAS __attribute__((address_space(3)))
; __device__ __forceinline__ void prologue_phase(const Ptrs& P, LAS unsigned char* lds, int vcu, int G, int tid, int lane, int wave) {
;     ...
;         for (int j = 0; j < 8; ++j)
; #pragma unroll
;             for (int i = 0; i < 4; ++i) { const int k = 256 * j + 4 * lane + i; const f32x4 w0 = *(const LAS f32x4*)(wg + k * 8), w1 = *(const LAS f32x4*)(wg + k * 8 + 4); const float hv = v[j][i];
;                 a[0] += hv * w0.x; a[1] += hv * w0.y; a[2] += hv * w0.z; a[3] += hv * w0.w; a[4] += hv * w1.x; a[5] += hv * w1.y; a[6] += hv * w1.z; a[7] += hv * w1.w;
;                 if (i == 3) asm volatile("" ::: "memory"); }
; #pragma unroll
;         for (int q = 0; q < 8; ++q) a[q] = wave_sum(a[q]);
;         if (lane == 0) {
; #pragma unroll
;             for (int q = 0; q < 8; ++q) gates[(size_t)m * 8 + q] = a[q] + P.in[3][q]; }
	v_fmac_f32_e32 v92, v34, v40
	v_fmac_f32_e32 v83, v34, v41
	v_fmac_f32_e32 v82, v34, v42
	v_fmac_f32_e32 v64, v34, v43
	ds_read_b128 v[36:39], v90 offset:57440
	ds_read_b128 v[40:43], v90 offset:57456
	s_waitcnt lgkmcnt(1)
	v_fmac_f32_e32 v96, v35, v36
	v_fmac_f32_e32 v95, v35, v37
	v_fmac_f32_e32 v94, v35, v38
	v_fmac_f32_e32 v93, v35, v39
	s_waitcnt lgkmcnt(0)
	v_fmac_f32_e32 v92, v35, v40
	v_fmac_f32_e32 v83, v35, v41
	v_fmac_f32_e32 v82, v35, v42
	v_fmac_f32_e32 v64, v35, v43
	ds_bpermute_b32 v34, v84, v96
	ds_bpermute_b32 v36, v84, v95
	ds_bpermute_b32 v38, v84, v94
	ds_bpermute_b32 v40, v84, v93
	ds_bpermute_b32 v42, v84, v92
	ds_bpermute_b32 v44, v84, v83
	ds_bpermute_b32 v46, v84, v82
	ds_bpermute_b32 v48, v84, v64
	s_waitcnt lgkmcnt(7)
	v_add_f32_e32 v34, v96, v34
	s_waitcnt lgkmcnt(6)
	v_add_f32_e32 v36, v95, v36
	s_waitcnt lgkmcnt(5)
	v_add_f32_e32 v38, v94, v38
	s_waitcnt lgkmcnt(4)
	v_add_f32_e32 v40, v93, v40
	s_waitcnt lgkmcnt(3)
	v_add_f32_e32 v42, v92, v42
	s_waitcnt lgkmcnt(2)
	v_add_f32_e32 v44, v83, v44
	s_waitcnt lgkmcnt(1)
	v_add_f32_e32 v46, v82, v46
	s_waitcnt lgkmcnt(0)
	v_add_f32_e32 v48, v64, v48
	ds_bpermute_b32 v35, v85, v34
	ds_bpermute_b32 v37, v85, v36
	ds_bpermute_b32 v39, v85, v38
	ds_bpermute_b32 v41, v85, v40
	ds_bpermute_b32 v43, v85, v42
	ds_bpermute_b32 v45, v85, v44
	ds_bpermute_b32 v47, v85, v46
	ds_bpermute_b32 v49, v85, v48
	s_waitcnt lgkmcnt(7)
	v_add_f32_e32 v34, v34, v35
	s_waitcnt lgkmcnt(6)
	v_add_f32_e32 v36, v36, v37
	s_waitcnt lgkmcnt(5)
	v_add_f32_e32 v38, v38, v39
	s_waitcnt lgkmcnt(4)
	v_add_f32_e32 v40, v40, v41
	s_waitcnt lgkmcnt(3)
	v_add_f32_e32 v42, v42, v43
	s_waitcnt lgkmcnt(2)
	v_add_f32_e32 v44, v44, v45
	s_waitcnt lgkmcnt(1)
	v_add_f32_e32 v46, v46, v47
	s_waitcnt lgkmcnt(0)
	v_add_f32_e32 v48, v48, v49
	ds_bpermute_b32 v35, v86, v34
	ds_bpermute_b32 v37, v86, v36
	ds_bpermute_b32 v39, v86, v38
	ds_bpermute_b32 v41, v86, v40
	ds_bpermute_b32 v43, v86, v42
	ds_bpermute_b32 v45, v86, v44
	ds_bpermute_b32 v47, v86, v46
	ds_bpermute_b32 v49, v86, v48
	s_waitcnt lgkmcnt(7)
	v_add_f32_e32 v34, v34, v35
	s_waitcnt lgkmcnt(6)
	v_add_f32_e32 v36, v36, v37
	s_waitcnt lgkmcnt(5)
	v_add_f32_e32 v38, v38, v39
	s_waitcnt lgkmcnt(4)
	v_add_f32_e32 v40, v40, v41
	s_waitcnt lgkmcnt(3)
	v_add_f32_e32 v42, v42, v43
	s_waitcnt lgkmcnt(2)
	v_add_f32_e32 v44, v44, v45
	s_waitcnt lgkmcnt(1)
	v_add_f32_e32 v46, v46, v47
	s_waitcnt lgkmcnt(0)
	v_add_f32_e32 v48, v48, v49
	ds_bpermute_b32 v35, v87, v34
	ds_bpermute_b32 v37, v87, v36
	ds_bpermute_b32 v39, v87, v38
	ds_bpermute_b32 v41, v87, v40
	ds_bpermute_b32 v43, v87, v42
	ds_bpermute_b32 v45, v87, v44
	ds_bpermute_b32 v47, v87, v46
	ds_bpermute_b32 v49, v87, v48
	s_waitcnt lgkmcnt(7)
	v_add_f32_e32 v34, v34, v35
	s_waitcnt lgkmcnt(6)
	v_add_f32_e32 v36, v36, v37
	s_waitcnt lgkmcnt(5)
	v_add_f32_e32 v38, v38, v39
	s_waitcnt lgkmcnt(4)
	v_add_f32_e32 v40, v40, v41
	s_waitcnt lgkmcnt(3)
	v_add_f32_e32 v42, v42, v43
	s_waitcnt lgkmcnt(2)
	v_add_f32_e32 v44, v44, v45
	s_waitcnt lgkmcnt(1)
	v_add_f32_e32 v46, v46, v47
	s_waitcnt lgkmcnt(0)
	v_add_f32_e32 v48, v48, v49
	ds_bpermute_b32 v35, v88, v34
	ds_bpermute_b32 v37, v88, v36
	ds_bpermute_b32 v39, v88, v38
	ds_bpermute_b32 v41, v88, v40
	ds_bpermute_b32 v43, v88, v42
	ds_bpermute_b32 v45, v88, v44
	ds_bpermute_b32 v47, v88, v46
	ds_bpermute_b32 v49, v88, v48
	s_waitcnt lgkmcnt(7)
	v_add_f32_e32 v34, v34, v35
	s_waitcnt lgkmcnt(6)
	v_add_f32_e32 v36, v36, v37
	s_waitcnt lgkmcnt(5)
	v_add_f32_e32 v38, v38, v39
	s_waitcnt lgkmcnt(4)
	v_add_f32_e32 v40, v40, v41
	s_waitcnt lgkmcnt(3)
	v_add_f32_e32 v42, v42, v43
	s_waitcnt lgkmcnt(2)
	v_add_f32_e32 v44, v44, v45
	s_waitcnt lgkmcnt(1)
	v_add_f32_e32 v46, v46, v47
	s_waitcnt lgkmcnt(0)
	v_add_f32_e32 v48, v48, v49
	ds_bpermute_b32 v35, v89, v34
	ds_bpermute_b32 v37, v89, v36
	ds_bpermute_b32 v39, v89, v38
	ds_bpermute_b32 v41, v89, v40
	ds_bpermute_b32 v43, v89, v42
	ds_bpermute_b32 v45, v89, v44
	ds_bpermute_b32 v47, v89, v46
	ds_bpermute_b32 v49, v89, v48
	s_and_saveexec_b64 s[4:5], s[0:1]
	s_cbranch_execz .LBB0_51
	v_mov_b32_e32 v50, v148
	s_waitcnt lgkmcnt(7)
	v_add_f32_e32 v34, v34, v35
	s_add_u32 s18, s34, s8
	s_addc_u32 s19, s35, s9
	s_waitcnt lgkmcnt(6)
	v_add_f32_e32 v35, v36, v37
	s_waitcnt vmcnt(0)
	v_add_f32_e32 v34, v34, v50
	global_store_dword v91, v34, s[18:19]
	v_mov_b32_e32 v34, v149
	s_nop 0
	v_add_f32_e32 v34, v35, v34
	global_store_dword v91, v34, s[18:19] offset:4
	v_mov_b32_e32 v34, v150
	s_waitcnt lgkmcnt(5)
	v_add_f32_e32 v35, v38, v39
	s_nop 0
	v_add_f32_e32 v34, v35, v34
	global_store_dword v91, v34, s[18:19] offset:8
	v_mov_b32_e32 v34, v151
	s_waitcnt lgkmcnt(4)
	v_add_f32_e32 v35, v40, v41
	s_nop 0
	v_add_f32_e32 v34, v35, v34
	global_store_dword v91, v34, s[18:19] offset:12
	v_mov_b32_e32 v34, v152
	s_waitcnt lgkmcnt(3)
	v_add_f32_e32 v35, v42, v43
	s_nop 0
	v_add_f32_e32 v34, v35, v34
	global_store_dword v91, v34, s[18:19] offset:16
	v_mov_b32_e32 v34, v153
	s_waitcnt lgkmcnt(2)
	v_add_f32_e32 v35, v44, v45
	s_nop 0
	v_add_f32_e32 v34, v35, v34
	global_store_dword v91, v34, s[18:19] offset:20
	v_mov_b32_e32 v34, v154
	s_waitcnt lgkmcnt(1)
	v_add_f32_e32 v35, v46, v47
	s_nop 0
	v_add_f32_e32 v34, v35, v34
	global_store_dword v91, v34, s[18:19] offset:24
	v_mov_b32_e32 v34, v155
	s_waitcnt lgkmcnt(0)
	v_add_f32_e32 v35, v48, v49
	s_nop 0
	v_add_f32_e32 v34, v35, v34
	global_store_dword v91, v34, s[18:19] offset:28
	s_branch .LBB0_51
